# GQA loop: K/V tile prefetch addressed as SGPR base + lane offset (no per-tile 64-bit VALU adds), on top of PV-read hoist, in-proj no-setprio + address hoist, sc1 epilogue stores
# speedup vs baseline: 1.0047x; 1.0040x over previous
; __device__ __forceinline__ int opaque_v(int v) { asm volatile("" : "+v"(v)); return v; }
; __global__ void __launch_bounds__(512) mega(Args a) {
;     ...
;       for (int i = 0;; ++i) {
;         const int un = i * G + cu; if (un >= NB * 8 * 32) break;
;         const int h = un & 7, qb = (un >> 3) & 31, b = un >> 8;
;         __syncthreads();
;         att::Unit U{};
;         const size_t tq = (size_t)b * SEQ + qb * 256;
;         U.Q = QBc + ((size_t)(b * 8 + h) * SEQ + qb * 256) * 128; U.K = KBc + (size_t)(b * 2 + (h >> 2)) * SEQ * 128; U.V = VBc + (size_t)(b * 2 + (h >> 2)) * SEQ * 128;
;         U.ldq = 128; U.ldk = 128; U.NT = SEQ / 64;
;         U.O = Y + tq * YW + 1024 + h * 128; U.ldo = YW; U.Z = PROJ + tq * NIN + C_ZB + h * 128; U.ldz = NIN;
;         att::attn_body<0, 2, false>(U, shm, opaque_v(tid));
.LBB0_195:
	s_or_b64 exec, exec, s[2:3]
	s_cmpk_gt_i32 s57, 0x1ff
	s_cbranch_scc1 .LBB0_217
	s_add_u32 s17, s0, 0x42000000
	s_addc_u32 s25, s1, 0
	s_add_u32 s58, s0, 0x44000000
	s_addc_u32 s59, s1, 0
	s_add_u32 s60, s0, 0x44800000
	s_addc_u32 s61, s1, 0
	v_readlane_b32 s0, v251, 4
	s_add_u32 s10, s0, s28
	v_readlane_b32 s0, v251, 5
	s_addc_u32 s11, s0, 0
	s_mov_b32 s40, 0
	s_mov_b32 s28, s57
	s_mov_b32 s0, s57
	s_mov_b32 s62, 0
	v_writelane_b32 v250, s4, 16
	v_writelane_b32 v250, s5, 17
	v_writelane_b32 v250, s6, 18
	v_writelane_b32 v250, s7, 19
	v_writelane_b32 v250, s66, 20
	v_writelane_b32 v250, s67, 21
	s_branch .LBB0_198

; #define SBAR() __builtin_amdgcn_sched_barrier(0)
; template <int MODE, int SDEPTH, bool SIMPLE>
; __device__ __forceinline__ void attn_body(const Unit& U, char* lds, const int tid) {
;     ...
;   const bf16_t* Qw = U.Q + (long)(wid * QBLK + r32) * U.ldq + hi * 8;
; #pragma unroll
;   for (int d0 = 0; d0 < 8; ++d0) qr[d0] = *reinterpret_cast<const bf16x8*>(Qw + d0 * 16);
;   const int sr = tid >> 4, sc = (tid & 15) * 8, vst0 = v_st(sr, sc), vst1 = v_st(32 + sr, sc);
;   const int vb0 = (int)(uintptr_t)V_lds + v_rd_base(lane);
;   const bf16_t* Kh = U.K; const bf16_t* Vh = U.V; const int LDK = U.ldk;
;   struct { bf16x8 vs0, vs1, ks0, ks1; } sr_[SDEPTH];
;     ...
;   bf16x8 pa0, pa1, pa2, pa3; const int NT = U.NT;
;   if constexpr (SIMPLE) {
;     f32x16 p0, p1; float mn, al;
;     SLOAD(0, 0);
;     for (int j = 0; j < NT; ++j) {
;       asm volatile("s_waitcnt vmcnt(0)" ::: "memory"); __syncthreads(); SWRITE(0, 0);
;       if (j + 1 < NT) SLOAD(0, (j + 1) * KVBLK);
;       __syncthreads();
;       bool act = true;
;       if constexpr (MODE == 1) { const int qrow = U.qr + (wid >> 1), kr = U.kr0 + j, st = min(max(qrow - 4, 0), 120); act = (kr >= st) && (kr < st + 8); }
;       if constexpr (MODE == 2) { const int q0 = U.i0 + wid * 32, t0 = U.k0 + j * 64; act = (t0 + 63 >= q0 - 64) && (t0 <= q0 + 31 + 64); }
;       if (act) {
;         qkt(p0, p1, K_lds, qr, r32, hi); amask<MODE>(p0, p1, j, U, wid, r32, hi, tbl);
;         partialSM(p0, p1, m_reg, mn, al); finishSM(p0, p1, al, l_reg, pa0, pa1, pa2, pa3);
;         RESC(al); SBAR();
;         pv_d0(o, vb0, pa0, pa1, pa2, pa3);
;       }
;     }
;   } else {
;   f32x16 pA0, pA1, pB0, pB1; float mnA, mnB, alA, alB;
;   constexpr int SE = 0, SO = SDEPTH - 1;
;   SLOAD(SE, 0); asm volatile("s_waitcnt vmcnt(0)" ::: "memory"); SWRITE(0, SE); __syncthreads();
; __global__ void __launch_bounds__(512) mega(Args a) {
;     ...
;         const int un = i * G + cu; if (un >= NB * 8 * 32) break;
;         const int h = un & 7, qb = (un >> 3) & 31, b = un >> 8;
;         __syncthreads();
;         att::Unit U{};
;         const size_t tq = (size_t)b * SEQ + qb * 256;
;         U.Q = QBc + ((size_t)(b * 8 + h) * SEQ + qb * 256) * 128; U.K = KBc + (size_t)(b * 2 + (h >> 2)) * SEQ * 128; U.V = VBc + (size_t)(b * 2 + (h >> 2)) * SEQ * 128;
;         U.ldq = 128; U.ldk = 128; U.NT = SEQ / 64;
.LBB0_198:
	s_ashr_i32 s30, s0, 8
	s_lshl_b32 s1, s0, 5
	s_and_b32 s16, s0, 7
	s_and_b32 s19, s1, 0x1f00
	s_lshl_b32 s1, s30, 3
	s_or_b32 s2, s1, s16
	s_ashr_i32 s3, s2, 31
	s_bfe_u32 s15, s28, 0x10002
	s_lshl_b64 s[2:3], s[2:3], 21
	s_add_u32 s1, s17, s2
	s_addc_u32 s2, s25, s3
	s_lshl_b32 s3, s19, 8
	s_add_u32 s36, s1, s3
	s_addc_u32 s37, s2, 0
	s_lshl_b32 s21, s30, 1
	s_bfe_u32 s0, s0, 0x10002
	s_or_b32 s0, s21, s0
	s_ashr_i32 s1, s0, 31
	s_waitcnt vmcnt(0)
	v_mov_b32_e32 v52, v177
	s_barrier
	s_lshl_b64 s[2:3], s[0:1], 21
	s_add_u32 s0, s58, s2
	v_ashrrev_i32_e32 v16, 4, v52
	v_lshlrev_b32_e32 v22, 3, v52
	v_add_u32_e32 v18, 32, v16
	s_addc_u32 s1, s59, s3
	v_and_b32_e32 v176, 0x78, v22
	v_ashrrev_i32_e32 v17, 31, v16
	v_ashrrev_i32_e32 v19, 31, v18
	s_add_u32 s2, s60, s2
	v_lshlrev_b32_e32 v23, 1, v176
	v_lshlrev_b64 v[48:49], 8, v[16:17]
	v_lshlrev_b64 v[12:13], 8, v[18:19]
	s_addc_u32 s3, s61, s3
	v_or_b32_e32 v50, v48, v23
	v_mov_b32_e32 v51, v49
	v_or_b32_e32 v12, v12, v23
	v_lshl_add_u64 v[0:1], s[2:3], 0, v[50:51]
	v_lshl_add_u64 v[4:5], s[2:3], 0, v[12:13]
	global_load_dwordx4 v[0:3], v[0:1], off
	s_nop 0
	global_load_dwordx4 v[4:7], v[4:5], off
	v_lshl_add_u64 v[8:9], s[0:1], 0, v[50:51]
	v_ashrrev_i32_e32 v184, 6, v52
	global_load_dwordx4 v[8:11], v[8:9], off
	v_lshl_add_u64 v[12:13], s[0:1], 0, v[12:13]
	v_and_b32_e32 v183, 31, v52
	v_lshlrev_b32_e32 v180, 5, v184
	global_load_dwordx4 v[12:15], v[12:13], off
	v_or_b32_e32 v20, v180, v183
	v_ashrrev_i32_e32 v21, 31, v20
	v_bfe_u32 v182, v52, 5, 1
	v_lshlrev_b64 v[20:21], 8, v[20:21]
	v_lshl_add_u64 v[20:21], s[36:37], 0, v[20:21]
	v_lshlrev_b32_e32 v192, 4, v182
	v_lshl_add_u64 v[20:21], v[20:21], 0, v[192:193]
	global_load_dwordx4 v[116:119], v[20:21], off
	global_load_dwordx4 v[112:115], v[20:21], off offset:32
	global_load_dwordx4 v[124:127], v[20:21], off offset:64
	global_load_dwordx4 v[120:123], v[20:21], off offset:96
	global_load_dwordx4 v[108:111], v[20:21], off offset:128
	global_load_dwordx4 v[104:107], v[20:21], off offset:160
	global_load_dwordx4 v[100:103], v[20:21], off offset:192
	global_load_dwordx4 v[96:99], v[20:21], off offset:224
	v_and_b32_e32 v19, 0xfffff0, v16
	v_lshlrev_b32_e32 v24, 1, v16
	v_lshrrev_b32_e32 v25, 1, v16
	v_and_b32_e32 v26, 3, v16
	v_and_or_b32 v19, v24, 8, v19
	v_and_or_b32 v24, v25, 4, v26
	v_and_b32_e32 v25, 0xfffff0, v18
	v_lshlrev_b32_e32 v26, 1, v18
	v_and_b32_e32 v17, 0x70, v52
	v_bfe_u32 v22, v22, 5, 2
	v_lshlrev_b32_e32 v16, 8, v16
	v_lshrrev_b32_e32 v19, 1, v19
	v_and_or_b32 v25, v26, 8, v25
	v_bitop3_b32 v16, v23, v16, v17 bitop3:0xde
	v_or_b32_e32 v19, v19, v22
	v_lshrrev_b32_e32 v25, 1, v25
	v_lshlrev_b32_e32 v24, 6, v24
	v_and_b32_e32 v27, 48, v23
	v_add_u32_e32 v190, 0, v16
	v_lshlrev_b32_e32 v16, 9, v19
	v_or_b32_e32 v19, v25, v22
	v_or3_b32 v16, v16, v24, v27
	v_lshlrev_b32_e32 v19, 9, v19
	v_lshlrev_b32_e32 v53, 4, v52
	v_lshlrev_b32_e32 v18, 8, v18
	v_or3_b32 v19, v19, v24, v27
	v_add_u32_e32 v191, 0, v16
	v_add_u32_e32 v202, 0, v19
	s_waitcnt vmcnt(0)
	v_and_b32_e32 v181, 63, v52
	s_add_i32 s22, 0, 0x11800
	s_mov_b64 s[26:27], 0x4000
	s_mov_b32 s41, s40
	v_lshl_add_u64 v[62:63], v[50:51], 0, s[26:27]
	s_mov_b64 s[26:27], 0x6000
	s_mov_b32 s42, s40
	s_mov_b32 s43, s40
	s_waitcnt vmcnt(11)
	ds_write_b128 v191, v[0:3]
	s_waitcnt vmcnt(10)
	ds_write_b128 v202, v[4:7]
	s_waitcnt vmcnt(9)
	ds_write_b128 v190, v[8:11] offset:32768
	v_bitop3_b32 v0, v23, v18, v17 bitop3:0xde
	v_lshlrev_b32_e32 v8, 8, v183
	v_and_b32_e32 v9, 0x70, v53
	v_add_u32_e32 v203, 0, v0
	v_bitop3_b32 v0, v192, v8, v9 bitop3:0xde
	v_add_u32_e32 v204, 0, v0
	s_waitcnt vmcnt(8)
	ds_write_b128 v203, v[12:15] offset:32768
	s_waitcnt lgkmcnt(0)
	s_barrier
	ds_read_b128 v[0:3], v204 offset:32768
	ds_read_b128 v[4:7], v204 offset:40960
	s_waitcnt vmcnt(7) lgkmcnt(1)
	v_mfma_f32_32x32x16_bf16 v[32:47], v[0:3], v[116:119], 0
	v_or_b32_e32 v0, 32, v192
	v_bitop3_b32 v0, v0, v8, v9 bitop3:0xde
	v_add_u32_e32 v211, 0, v0
	v_lshlrev_b32_e32 v10, 3, v181
	v_lshlrev_b32_e32 v12, 1, v52
	s_mov_b32 s44, s40
	s_mov_b32 s45, s40
	s_waitcnt lgkmcnt(0)
	v_mfma_f32_32x32x16_bf16 v[16:31], v[4:7], v[116:119], 0
	ds_read_b128 v[0:3], v211 offset:32768
	ds_read_b128 v[4:7], v211 offset:40960
	s_mov_b32 s46, s40
	s_mov_b32 s47, s40
	s_mov_b32 s48, s40
	s_mov_b32 s49, s40
	s_mov_b32 s50, s40
	s_mov_b32 s51, s40
	s_waitcnt vmcnt(6) lgkmcnt(1)
	v_mfma_f32_32x32x16_bf16 v[32:47], v[0:3], v[112:115], v[32:47]
	v_or_b32_e32 v0, 64, v192
	v_bitop3_b32 v0, v0, v8, v9 bitop3:0xde
	v_add_u32_e32 v210, 0, v0
	s_mov_b32 s52, s40
	s_mov_b32 s53, s40
	s_mov_b32 s54, s40
	s_mov_b32 s55, s40
	s_waitcnt lgkmcnt(0)
	v_mfma_f32_32x32x16_bf16 v[16:31], v[4:7], v[112:115], v[16:31]
	ds_read_b128 v[0:3], v210 offset:32768
	ds_read_b128 v[4:7], v210 offset:40960
	v_lshl_add_u64 v[64:65], v[50:51], 0, s[26:27]
	v_lshl_add_u64 v[58:59], s[2:3], 0, v[64:65]
	v_lshl_add_u64 v[66:67], s[0:1], 0, v[64:65]
	s_mov_b64 s[26:27], 0xa000
	s_cmp_lg_u32 0, -1
	s_mov_b32 s20, 1
	s_waitcnt vmcnt(5) lgkmcnt(1)
	v_mfma_f32_32x32x16_bf16 v[32:47], v[0:3], v[124:127], v[32:47]
	v_or_b32_e32 v0, 0x60, v192
	v_bitop3_b32 v0, v0, v8, v9 bitop3:0xde
	v_add_u32_e32 v208, 0, v0
	v_cmp_gt_u32_e64 s[36:37], 32, v181
	v_mov_b32_e32 v187, 0
	s_waitcnt lgkmcnt(0)
	v_mfma_f32_32x32x16_bf16 v[16:31], v[4:7], v[124:127], v[16:31]
	ds_read_b128 v[0:3], v208 offset:32768
	ds_read_b128 v[4:7], v208 offset:40960
	s_waitcnt vmcnt(4) lgkmcnt(1)
	v_mfma_f32_32x32x16_bf16 v[32:47], v[0:3], v[120:123], v[32:47]
	v_or_b32_e32 v0, 0x80, v192
	v_bitop3_b32 v0, v0, v8, v9 bitop3:0xde
	v_add_u32_e32 v206, 0, v0
	s_waitcnt lgkmcnt(0)
; #define SLOAD(i, k0) do { sr_[i].vs0 = *(const bf16x8*)(&Vh[(long)((k0) + sr) * LDK + sc]); sr_[i].vs1 = *(const bf16x8*)(&Vh[(long)((k0) + 32 + sr) * LDK + sc]); \
;     sr_[i].ks0 = *(const bf16x8*)(&Kh[(long)((k0) + sr) * LDK + sc]); sr_[i].ks1 = *(const bf16x8*)(&Kh[(long)((k0) + 32 + sr) * LDK + sc]); } while (0)
; __device__ __forceinline__ void partialSM(f32x16& p0, f32x16& p1, float& m_reg, float& mn, float& alpha) {
;   constexpr float C = SCALE * 1.4426950408889634f;
;   float pmax = p0[0];
; #pragma unroll
;   for (int r = 1; r < 16; ++r) pmax = fmaxf(pmax, p0[r]);
; #pragma unroll
;   for (int r = 0; r < 16; ++r) pmax = fmaxf(pmax, p1[r]);
;   { auto rr = __builtin_amdgcn_permlane32_swap(__float_as_uint(pmax), __float_as_uint(pmax), false, false);
;     pmax = fmaxf(__uint_as_float(rr[0]), __uint_as_float(rr[1])); }
;   if (__builtin_expect(__all(pmax - m_reg <= THR / SCALE), 1)) { mn = m_reg; alpha = 1.f; }
;   else { mn = fmaxf(m_reg, pmax); alpha = __builtin_amdgcn_exp2f((m_reg - mn) * C); m_reg = mn; }
;   float mnC = -mn * C;
; #pragma unroll
;   for (int r = 0; r < 16; ++r) p0[r] = fmaf(p0[r], C, mnC);
; #pragma unroll
;   for (int r = 0; r < 16; ++r) p1[r] = fmaf(p1[r], C, mnC);
; template <int MODE, int SDEPTH, bool SIMPLE>
; __device__ __forceinline__ void attn_body(const Unit& U, char* lds, const int tid) {
;     ...
;   qkt(pA0, pA1, K_lds, qr, r32, hi); amask<MODE>(pA0, pA1, 0, U, wid, r32, hi, tbl); partialSM(pA0, pA1, m_reg, mnA, alA);
;   SLOAD(SO, KVBLK); if constexpr (SDEPTH == 2) { if (2 < NT) SLOAD(SE, 2 * KVBLK); }
	v_mfma_f32_32x32x16_bf16 v[16:31], v[4:7], v[120:123], v[16:31]
	ds_read_b128 v[0:3], v206 offset:32768
	ds_read_b128 v[4:7], v206 offset:40960
	s_waitcnt vmcnt(3) lgkmcnt(1)
	v_mfma_f32_32x32x16_bf16 v[32:47], v[0:3], v[108:111], v[32:47]
	v_or_b32_e32 v0, 0xa0, v192
	v_bitop3_b32 v0, v0, v8, v9 bitop3:0xde
	v_add_u32_e32 v205, 0, v0
	ds_read_b128 v[0:3], v205 offset:32768
	s_waitcnt lgkmcnt(1)
	v_mfma_f32_32x32x16_bf16 v[16:31], v[4:7], v[108:111], v[16:31]
	v_and_b32_e32 v4, 0x3fffffc0, v52
	v_lshl_add_u32 v185, v4, 2, s22
	ds_read_b128 v[4:7], v205 offset:40960
	s_cselect_b32 s22, 0, 0
	v_lshl_add_u32 v186, v183, 2, v185
	s_waitcnt vmcnt(2) lgkmcnt(1)
	v_mfma_f32_32x32x16_bf16 v[32:47], v[0:3], v[104:107], v[32:47]
	v_and_b32_e32 v0, 0xc0, v53
	v_and_or_b32 v11, v10, 24, v0
	v_or_b32_e32 v0, 0xc0, v192
	v_bitop3_b32 v0, v0, v8, v9 bitop3:0xde
	v_add_u32_e32 v207, 0, v0
	ds_read_b128 v[0:3], v207 offset:32768
	s_waitcnt lgkmcnt(1)
	v_mfma_f32_32x32x16_bf16 v[16:31], v[4:7], v[104:107], v[16:31]
	v_and_b32_e32 v4, 32, v12
	v_and_b32_e32 v5, 0x100, v10
	v_or3_b32 v53, v11, v4, v5
	ds_read_b128 v[4:7], v207 offset:40960
	v_add_u32_e32 v189, s22, v53
	s_waitcnt vmcnt(1) lgkmcnt(1)
	v_mfma_f32_32x32x16_bf16 v[32:47], v[0:3], v[100:103], v[32:47]
	v_or_b32_e32 v0, 0xe0, v192
	v_bitop3_b32 v0, v0, v8, v9 bitop3:0xde
	v_add_u32_e32 v209, 0, v0
	ds_read_b128 v[0:3], v209 offset:32768
	ds_read_b128 v[54:57], v209 offset:40960
	s_waitcnt lgkmcnt(2)
	v_mfma_f32_32x32x16_bf16 v[16:31], v[4:7], v[100:103], v[16:31]
	s_waitcnt vmcnt(0) lgkmcnt(1)
	v_mfma_f32_32x32x16_bf16 v[32:47], v[0:3], v[96:99], v[32:47]
	v_mov_b64_e32 v[0:1], s[40:41]
	v_mov_b64_e32 v[2:3], s[42:43]
	v_mov_b64_e32 v[4:5], s[44:45]
	v_mov_b64_e32 v[6:7], s[46:47]
	v_mov_b64_e32 v[8:9], s[48:49]
	v_mov_b64_e32 v[10:11], s[50:51]
	v_mov_b64_e32 v[12:13], s[52:53]
	s_waitcnt lgkmcnt(0)
	v_mfma_f32_32x32x16_bf16 v[16:31], v[54:57], v[96:99], v[16:31]
	s_nop 2
	v_max_f32_e32 v54, v33, v33
	v_max_f32_e32 v55, v32, v32
	v_max_f32_e32 v54, v55, v54
	v_max3_f32 v54, v54, v34, v35
	v_max3_f32 v54, v54, v36, v37
	v_max3_f32 v54, v54, v38, v39
	v_max3_f32 v54, v54, v40, v41
	v_max3_f32 v54, v54, v42, v43
	v_max3_f32 v54, v54, v44, v45
	v_max3_f32 v54, v54, v46, v47
	v_max3_f32 v70, v54, v16, v17
	v_max3_f32 v70, v70, v18, v19
	v_max3_f32 v70, v70, v20, v21
	v_max3_f32 v70, v70, v22, v23
	v_max3_f32 v70, v70, v24, v25
	v_max3_f32 v70, v70, v26, v27
	v_mov_b64_e32 v[14:15], s[54:55]
	v_lshl_add_u64 v[54:55], s[2:3], 0, v[62:63]
	v_lshl_add_u64 v[62:63], s[0:1], 0, v[62:63]
	v_max3_f32 v70, v70, v28, v29
	s_mov_b64 s[44:45], 0x8000
	global_load_dwordx4 v[54:57], v[54:55], off
	s_nop 0
	global_load_dwordx4 v[58:61], v[58:59], off
	s_nop 0
	global_load_dwordx4 v[62:65], v[62:63], off
	s_nop 0
	global_load_dwordx4 v[66:69], v[66:67], off
	v_max3_f32 v76, v70, v30, v31
	v_lshl_add_u64 v[70:71], v[50:51], 0, s[44:45]
	v_lshl_add_u64 v[72:73], s[2:3], 0, v[70:71]
	v_lshl_add_u64 v[50:51], v[50:51], 0, s[26:27]
	v_lshl_add_u64 v[70:71], s[0:1], 0, v[70:71]
	v_lshl_add_u64 v[74:75], s[2:3], 0, v[50:51]
	global_load_dwordx4 v[128:131], v[72:73], off
	global_load_dwordx4 v[136:139], v[74:75], off
	v_lshl_add_u64 v[50:51], s[0:1], 0, v[50:51]
	global_load_dwordx4 v[132:135], v[70:71], off
	global_load_dwordx4 v[140:143], v[50:51], off
	v_mov_b32_e32 v77, v76
	s_nop 1
	v_permlane32_swap_b32_e32 v76, v77
	v_max_f32_e32 v50, v77, v77
	v_max_f32_e32 v51, v76, v76
	v_max_f32_e32 v50, v51, v50
	v_add_f32_e32 v51, 0x7149f2ca, v50
	v_max_f32_e32 v50, 0xf149f2ca, v50
	v_cmp_ge_f32_e32 vcc, s18, v51
	v_sub_f32_e32 v51, 0xf149f2ca, v50
	v_mul_f32_e32 v51, 0x3e0293ee, v51
	v_exp_f32_e32 v51, v51
	s_cmp_eq_u64 vcc, exec
	s_cselect_b64 vcc, -1, 0
	v_cndmask_b32_e32 v164, v50, v228, vcc
	v_mul_f32_e32 v50, 0xbe0293ee, v164
	s_or_b32 s0, s15, s21
	v_cndmask_b32_e64 v212, v51, 1.0, vcc
	v_mov_b32_e32 v51, v50
	s_ashr_i32 s1, s0, 31
	v_fmamk_f32 v32, v32, 0x3e0293ee, v50
	v_fmamk_f32 v33, v33, 0x3e0293ee, v50
	v_fmamk_f32 v34, v34, 0x3e0293ee, v50
	v_fmamk_f32 v35, v35, 0x3e0293ee, v50
	v_fmamk_f32 v36, v36, 0x3e0293ee, v50
	v_fmamk_f32 v37, v37, 0x3e0293ee, v50
	v_fmamk_f32 v38, v38, 0x3e0293ee, v50
	v_fmamk_f32 v39, v39, 0x3e0293ee, v50
	v_fmamk_f32 v40, v40, 0x3e0293ee, v50
	v_fmamk_f32 v41, v41, 0x3e0293ee, v50
	v_fmamk_f32 v42, v42, 0x3e0293ee, v50
	v_fmamk_f32 v43, v43, 0x3e0293ee, v50
	v_fmamk_f32 v44, v44, 0x3e0293ee, v50
	v_fmamk_f32 v45, v45, 0x3e0293ee, v50
	v_fmamk_f32 v46, v46, 0x3e0293ee, v50
	v_fmac_f32_e32 v51, 0x3e0293ee, v47
	s_lshl_b64 s[0:1], s[0:1], 21
	v_pk_fma_f32 v[154:155], v[18:19], s[12:13], v[50:51] op_sel_hi:[1,0,0]
	v_pk_fma_f32 v[156:157], v[16:17], s[12:13], v[50:51] op_sel_hi:[1,0,0]
	v_exp_f32_e32 v161, v32
	v_exp_f32_e32 v162, v33
	v_exp_f32_e32 v174, v34
	v_exp_f32_e32 v175, v35
	v_exp_f32_e32 v216, v36
	v_exp_f32_e32 v219, v37
	v_exp_f32_e32 v163, v38
	v_exp_f32_e32 v173, v39
	v_exp_f32_e32 v168, v40
	v_exp_f32_e32 v170, v41
	v_exp_f32_e32 v171, v42
	v_exp_f32_e32 v172, v43
	v_exp_f32_e32 v165, v44
	v_exp_f32_e32 v166, v45
	v_exp_f32_e32 v167, v46
	v_exp_f32_e32 v169, v51
	v_lshl_add_u64 v[16:17], s[0:1], 0, v[48:49]
	v_and_b32_e32 v18, 15, v52
	s_waitcnt vmcnt(4)
	s_addk_i32 s22, 0x4000
	v_lshl_or_b32 v16, v18, 4, v16
	v_pk_fma_f32 v[150:151], v[30:31], s[12:13], v[50:51] op_sel_hi:[1,0,0]
	v_pk_fma_f32 v[152:153], v[28:29], s[12:13], v[50:51] op_sel_hi:[1,0,0]
	v_pk_fma_f32 v[158:159], v[26:27], s[12:13], v[50:51] op_sel_hi:[1,0,0]
	v_pk_fma_f32 v[144:145], v[24:25], s[12:13], v[50:51] op_sel_hi:[1,0,0]
	v_pk_fma_f32 v[146:147], v[22:23], s[12:13], v[50:51] op_sel_hi:[1,0,0]
	v_pk_fma_f32 v[148:149], v[20:21], s[12:13], v[50:51] op_sel_hi:[1,0,0]
	s_waitcnt vmcnt(7)
; #define SBAR() __builtin_amdgcn_sched_barrier(0)
; #define SWRITE(b, i) do { *(bf16x8*)(V_lds + (b) * SHM_V + vst0) = sr_[i].vs0;          \
;     *(bf16x8*)(V_lds + (b) * SHM_V + vst1) = sr_[i].vs1; int kc = sc * 2;               \
;     *(bf16x8*)(K_lds + (b) * SHM_K + KSWZ(sr, kc)) = sr_[i].ks0;                       \
;     *(bf16x8*)(K_lds + (b) * SHM_K + KSWZ(32 + sr, kc)) = sr_[i].ks1; } while (0)
; #define SWAIT() do { if constexpr (SDEPTH == 2) asm volatile("s_waitcnt vmcnt(4)" ::: "memory"); else asm volatile("s_waitcnt vmcnt(0)" ::: "memory"); } while (0)
; __device__ __forceinline__ void qkt(f32x16& p0, f32x16& p1, const char* Ks, const bf16x8* qr, int r32, int hi) {
;   p0 = f32x16{}; p1 = f32x16{};
; #pragma unroll
;   for (int d0 = 0; d0 < 8; ++d0) { int cb = (d0 * 16 + hi * 8) * 2;
;     bf16x8 b0 = *reinterpret_cast<const bf16x8*>(Ks + KSWZ(r32, cb));
;     bf16x8 b1 = *reinterpret_cast<const bf16x8*>(Ks + KSWZ(32 + r32, cb));
;     p0 = __builtin_amdgcn_mfma_f32_32x32x16_bf16(b0, qr[d0], p0, 0, 0, 0);
;     p1 = __builtin_amdgcn_mfma_f32_32x32x16_bf16(b1, qr[d0], p1, 0, 0, 0); }
; template <int MODE, int SDEPTH, bool SIMPLE>
; __device__ __forceinline__ void attn_body(const Unit& U, char* lds, const int tid) {
;     ...
;   SWAIT(); SWRITE(1, SO); __syncthreads();
;   for (int j = 1; j + 1 < NT; j += 2) {
;     SBAR(); qkt(pB0, pB1, K_lds + SHM_K, qr, r32, hi); amask<MODE>(pB0, pB1, j, U, wid, r32, hi, tbl);
;     finishSM(pA0, pA1, alA, l_reg, pa0, pa1, pa2, pa3); SBAR();
	ds_write_b128 v191, v[54:57] offset:16384
	s_waitcnt vmcnt(6)
	ds_write_b128 v202, v[58:61] offset:16384
	s_waitcnt vmcnt(5)
	ds_write_b128 v190, v[62:65] offset:49152
	s_waitcnt vmcnt(4)
	ds_write_b128 v203, v[66:69] offset:49152
	v_add_u32_e32 v188, s22, v53
	v_lshl_add_u64 v[178:179], s[10:11], 0, v[16:17]
	s_nop 0
	v_readfirstlane_b32 s66, v178
	v_readfirstlane_b32 s67, v179
	s_nop 1
	v_subrev_u32_e32 v178, s66, v178
	s_sub_u32 s6, s66, 0x6000
	s_subb_u32 s7, s67, 0
	s_sub_u32 s4, s6, 0x800000
	s_subb_u32 s5, s7, 0
	v_add_u32_e32 v179, 0x2000, v178
	v_mov_b64_e32 v[62:63], v[14:15]
	v_mov_b64_e32 v[46:47], v[14:15]
	v_mov_b64_e32 v[30:31], v[14:15]
	v_mov_b64_e32 v[60:61], v[12:13]
	v_mov_b64_e32 v[58:59], v[10:11]
	v_mov_b64_e32 v[56:57], v[8:9]
	v_mov_b64_e32 v[54:55], v[6:7]
	v_mov_b64_e32 v[52:53], v[4:5]
	v_mov_b64_e32 v[50:51], v[2:3]
	v_mov_b64_e32 v[48:49], v[0:1]
	v_mov_b64_e32 v[44:45], v[12:13]
	v_mov_b64_e32 v[42:43], v[10:11]
	v_mov_b64_e32 v[40:41], v[8:9]
	v_mov_b64_e32 v[38:39], v[6:7]
	v_mov_b64_e32 v[36:37], v[4:5]
	v_mov_b64_e32 v[34:35], v[2:3]
	v_mov_b64_e32 v[32:33], v[0:1]
	v_mov_b64_e32 v[28:29], v[12:13]
	v_mov_b64_e32 v[26:27], v[10:11]
	v_mov_b64_e32 v[24:25], v[8:9]
	v_mov_b64_e32 v[22:23], v[6:7]
	v_mov_b64_e32 v[20:21], v[4:5]
	v_mov_b64_e32 v[18:19], v[2:3]
	v_mov_b64_e32 v[16:17], v[0:1]
	s_waitcnt lgkmcnt(0)
	s_barrier
.LBB0_199:
	ds_read_b128 v[64:67], v204 offset:49152
	ds_read_b128 v[68:71], v204 offset:57344
	ds_read_b128 v[220:223], v211 offset:49152
	ds_read_b128 v[234:237], v211 offset:57344
	v_add_f32_e32 v160, 0, v161
	v_add_f32_e32 v160, v162, v160
	s_waitcnt lgkmcnt(3)
	v_mfma_f32_32x32x16_bf16 v[80:95], v[64:67], v[116:119], 0
	v_add_f32_e32 v160, v174, v160
	v_add_f32_e32 v160, v175, v160
	v_add_f32_e32 v160, v216, v160
	v_add_f32_e32 v160, v219, v160
	v_add_f32_e32 v160, v163, v160
	v_add_f32_e32 v160, v173, v160
	v_add_f32_e32 v160, v168, v160
	s_waitcnt lgkmcnt(2)
	v_mfma_f32_32x32x16_bf16 v[64:79], v[68:71], v[116:119], 0
	v_add_f32_e32 v160, v170, v160
	v_add_f32_e32 v160, v171, v160
	v_add_f32_e32 v160, v172, v160
	v_exp_f32_e32 v156, v156
	v_add_f32_e32 v160, v165, v160
	v_exp_f32_e32 v157, v157
	v_add_f32_e32 v160, v166, v160
	s_waitcnt lgkmcnt(1)
	v_mfma_f32_32x32x16_bf16 v[80:95], v[220:223], v[112:115], v[80:95]
	v_exp_f32_e32 v154, v154
	v_add_f32_e32 v160, v167, v160
	v_exp_f32_e32 v155, v155
	v_add_f32_e32 v160, v169, v160
	v_exp_f32_e32 v148, v148
	v_add_f32_e32 v160, v156, v160
	v_exp_f32_e32 v149, v149
	s_waitcnt lgkmcnt(0)
	v_mfma_f32_32x32x16_bf16 v[64:79], v[234:237], v[112:115], v[64:79]
	ds_read_b128 v[220:223], v210 offset:49152
	ds_read_b128 v[234:237], v210 offset:57344
	v_add_f32_e32 v160, v157, v160
	v_exp_f32_e32 v146, v146
	v_add_f32_e32 v160, v154, v160
	v_exp_f32_e32 v147, v147
	v_add_f32_e32 v160, v155, v160
	v_exp_f32_e32 v144, v144
	s_waitcnt lgkmcnt(1)
	v_mfma_f32_32x32x16_bf16 v[80:95], v[220:223], v[124:127], v[80:95]
	v_add_f32_e32 v160, v148, v160
	v_exp_f32_e32 v145, v145
	v_add_f32_e32 v160, v149, v160
	v_exp_f32_e32 v158, v158
	v_add_f32_e32 v160, v146, v160
	v_exp_f32_e32 v159, v159
	v_add_f32_e32 v160, v147, v160
	s_waitcnt lgkmcnt(0)
	v_mfma_f32_32x32x16_bf16 v[64:79], v[234:237], v[124:127], v[64:79]
	ds_read_b128 v[220:223], v208 offset:49152
	ds_read_b128 v[234:237], v208 offset:57344
	v_exp_f32_e32 v152, v152
	v_add_f32_e32 v160, v144, v160
	v_exp_f32_e32 v153, v153
	v_add_f32_e32 v160, v145, v160
	v_exp_f32_e32 v150, v150
	v_add_f32_e32 v160, v158, v160
	s_waitcnt lgkmcnt(1)
	v_mfma_f32_32x32x16_bf16 v[80:95], v[220:223], v[120:123], v[80:95]
	v_exp_f32_e32 v151, v151
	v_add_f32_e32 v160, v159, v160
	v_add_f32_e32 v160, v152, v160
	v_add_f32_e32 v160, v153, v160
	v_add_f32_e32 v160, v150, v160
	v_add_f32_e32 v213, v151, v160
	v_mov_b32_e32 v214, v213
	s_waitcnt lgkmcnt(0)
	v_mfma_f32_32x32x16_bf16 v[64:79], v[234:237], v[120:123], v[64:79]
	ds_read_b128 v[220:223], v206 offset:49152
	ds_read_b128 v[234:237], v206 offset:57344
	v_cvt_pk_bf16_f32 v160, v161, v162
	v_cvt_pk_bf16_f32 v162, v216, v219
	v_permlane32_swap_b32_e32 v213, v214
	v_cvt_pk_bf16_f32 v161, v174, v175
	v_cvt_pk_bf16_f32 v163, v163, v173
	s_waitcnt lgkmcnt(1)
	v_mfma_f32_32x32x16_bf16 v[80:95], v[220:223], v[108:111], v[80:95]
	v_permlane32_swap_b32_e32 v160, v162
	v_cvt_pk_bf16_f32 v170, v168, v170
	v_cvt_pk_bf16_f32 v171, v171, v172
	v_cvt_pk_bf16_f32 v172, v165, v166
	v_cvt_pk_bf16_f32 v173, v167, v169
	v_cvt_pk_bf16_f32 v166, v156, v157
	s_waitcnt lgkmcnt(0)
	v_mfma_f32_32x32x16_bf16 v[64:79], v[234:237], v[108:111], v[64:79]
	ds_read_b128 v[220:223], v205 offset:49152
	ds_read_b128 v[234:237], v205 offset:57344
	v_cvt_pk_bf16_f32 v167, v154, v155
	v_cvt_pk_bf16_f32 v168, v148, v149
	v_cvt_pk_bf16_f32 v169, v146, v147
	v_cvt_pk_bf16_f32 v216, v144, v145
	v_cvt_pk_bf16_f32 v217, v158, v159
	v_cvt_pk_bf16_f32 v218, v152, v153
	s_waitcnt lgkmcnt(1)
	v_mfma_f32_32x32x16_bf16 v[80:95], v[220:223], v[104:107], v[80:95]
	v_cvt_pk_bf16_f32 v219, v150, v151
	v_permlane32_swap_b32_e32 v161, v163
	v_permlane32_swap_b32_e32 v170, v172
	v_permlane32_swap_b32_e32 v171, v173
	s_waitcnt lgkmcnt(0)
	v_mfma_f32_32x32x16_bf16 v[64:79], v[234:237], v[104:107], v[64:79]
	ds_read_b64_tr_b16 v[144:145], v189 offset:0
	ds_read_b64_tr_b16 v[146:147], v189 offset:0x800
	ds_read_b64_tr_b16 v[148:149], v189 offset:0x1000
	ds_read_b64_tr_b16 v[150:151], v189 offset:0x1800
	ds_read_b64_tr_b16 v[152:153], v189 offset:0x2000
	ds_read_b64_tr_b16 v[154:155], v189 offset:0x2800
	ds_read_b64_tr_b16 v[156:157], v189 offset:0x3000
	ds_read_b64_tr_b16 v[158:159], v189 offset:0x3800
	ds_read_b128 v[220:223], v207 offset:49152
	ds_read_b128 v[234:237], v207 offset:57344
	v_permlane32_swap_b32_e32 v166, v168
	v_permlane32_swap_b32_e32 v167, v169
	v_permlane32_swap_b32_e32 v216, v218
	s_waitcnt lgkmcnt(1)
; #define SBAR() __builtin_amdgcn_sched_barrier(0)
; #define SLOAD(i, k0) do { sr_[i].vs0 = *(const bf16x8*)(&Vh[(long)((k0) + sr) * LDK + sc]); sr_[i].vs1 = *(const bf16x8*)(&Vh[(long)((k0) + 32 + sr) * LDK + sc]); \
;     sr_[i].ks0 = *(const bf16x8*)(&Kh[(long)((k0) + sr) * LDK + sc]); sr_[i].ks1 = *(const bf16x8*)(&Kh[(long)((k0) + 32 + sr) * LDK + sc]); } while (0)
; #define SWRITE(b, i) do { *(bf16x8*)(V_lds + (b) * SHM_V + vst0) = sr_[i].vs0;          \
;     *(bf16x8*)(V_lds + (b) * SHM_V + vst1) = sr_[i].vs1; int kc = sc * 2;               \
;     *(bf16x8*)(K_lds + (b) * SHM_K + KSWZ(sr, kc)) = sr_[i].ks0;                       \
;     *(bf16x8*)(K_lds + (b) * SHM_K + KSWZ(32 + sr, kc)) = sr_[i].ks1; } while (0)
; #define SWAIT() do { if constexpr (SDEPTH == 2) asm volatile("s_waitcnt vmcnt(4)" ::: "memory"); else asm volatile("s_waitcnt vmcnt(0)" ::: "memory"); } while (0)
; template <int D0> __device__ __forceinline__ void pv_one(f32x16& od, int vb, bf16x8 pa0, bf16x8 pa1, bf16x8 pa2, bf16x8 pa3) {
;   const s16x4 l0 = tr_read<v_rd_off(D0, 0, 0)>(vb), h0 = tr_read<v_rd_off(D0, 0, 1)>(vb), l1 = tr_read<v_rd_off(D0, 1, 0)>(vb), h1 = tr_read<v_rd_off(D0, 1, 1)>(vb);
;   const s16x4 l2 = tr_read<v_rd_off(D0, 2, 0)>(vb), h2 = tr_read<v_rd_off(D0, 2, 1)>(vb), l3 = tr_read<v_rd_off(D0, 3, 0)>(vb), h3 = tr_read<v_rd_off(D0, 3, 1)>(vb);
;   asm volatile("s_waitcnt lgkmcnt(0)" ::: "memory"); SBAR();
;     ...
;   od = __builtin_amdgcn_mfma_f32_32x32x16_bf16(pa0, PK(l0, h0), od, 0, 0, 0);
;   od = __builtin_amdgcn_mfma_f32_32x32x16_bf16(pa1, PK(l1, h1), od, 0, 0, 0);
;   od = __builtin_amdgcn_mfma_f32_32x32x16_bf16(pa2, PK(l2, h2), od, 0, 0, 0);
;   od = __builtin_amdgcn_mfma_f32_32x32x16_bf16(pa3, PK(l3, h3), od, 0, 0, 0);
;     ...
; }
; __device__ __forceinline__ void pv_d0(f32x16* o, int vb, bf16x8 pa0, bf16x8 pa1, bf16x8 pa2, bf16x8 pa3) {
;   pv_one<0>(o[0], vb, pa0, pa1, pa2, pa3); pv_one<1>(o[1], vb, pa0, pa1, pa2, pa3); pv_one<2>(o[2], vb, pa0, pa1, pa2, pa3); pv_one<3>(o[3], vb, pa0, pa1, pa2, pa3);
; template <int MODE, int SDEPTH, bool SIMPLE>
; __device__ __forceinline__ void attn_body(const Unit& U, char* lds, const int tid) {
;     ...
;     SLOAD(SO, (j + SDEPTH) * KVBLK); SBAR();
;     pv_d0(o, vb0, pa0, pa1, pa2, pa3); partialSM(pB0, pB1, m_reg, mnB, alB);
;     __syncthreads(); SWAIT(); SWRITE(0, SE);
;     RESC(alB); __syncthreads();
	v_mfma_f32_32x32x16_bf16 v[80:95], v[220:223], v[100:103], v[80:95]
	v_permlane32_swap_b32_e32 v217, v219
	s_waitcnt lgkmcnt(0)
	v_mfma_f32_32x32x16_bf16 v[64:79], v[234:237], v[100:103], v[64:79]
	ds_read_b128 v[220:223], v209 offset:49152
	ds_read_b128 v[234:237], v209 offset:57344
	s_waitcnt lgkmcnt(1)
	v_mfma_f32_32x32x16_bf16 v[80:95], v[220:223], v[96:99], v[80:95]
	s_waitcnt lgkmcnt(0)
	v_mfma_f32_32x32x16_bf16 v[64:79], v[234:237], v[96:99], v[64:79]
	s_waitcnt lgkmcnt(0)
	s_nop 0
	v_mfma_f32_32x32x16_bf16 v[0:15], v[160:163], v[144:147], v[0:15]
	ds_read_b64_tr_b16 v[220:221], v189 offset:0x200
	ds_read_b64_tr_b16 v[222:223], v189 offset:0xa00
	v_mfma_f32_32x32x16_bf16 v[0:15], v[170:173], v[148:151], v[0:15]
	ds_read_b64_tr_b16 v[234:235], v189 offset:0x1200
	ds_read_b64_tr_b16 v[236:237], v189 offset:0x1a00
	v_mfma_f32_32x32x16_bf16 v[0:15], v[166:169], v[152:155], v[0:15]
	ds_read_b64_tr_b16 v[238:239], v189 offset:0x2200
	ds_read_b64_tr_b16 v[240:241], v189 offset:0x2a00
	v_mfma_f32_32x32x16_bf16 v[0:15], v[216:219], v[156:159], v[0:15]
	ds_read_b64_tr_b16 v[242:243], v189 offset:0x3200
	ds_read_b64_tr_b16 v[244:245], v189 offset:0x3a00
	global_load_dwordx4 v[144:147], v178, s[6:7]
	global_load_dwordx4 v[148:151], v179, s[6:7]
	global_load_dwordx4 v[152:155], v178, s[4:5]
	global_load_dwordx4 v[156:159], v179, s[4:5]
	s_add_u32 s6, s6, 0x4000
	s_addc_u32 s7, s7, 0
	s_add_u32 s4, s4, 0x4000
	s_addc_u32 s5, s5, 0
	s_waitcnt lgkmcnt(0)
	v_mfma_f32_32x32x16_bf16 v[48:63], v[160:163], v[220:223], v[48:63]
	ds_read_b64_tr_b16 v[220:221], v189 offset:0x400
	ds_read_b64_tr_b16 v[222:223], v189 offset:0xc00
	v_mfma_f32_32x32x16_bf16 v[48:63], v[170:173], v[234:237], v[48:63]
	ds_read_b64_tr_b16 v[234:235], v189 offset:0x1400
	ds_read_b64_tr_b16 v[236:237], v189 offset:0x1c00
	v_mfma_f32_32x32x16_bf16 v[48:63], v[166:169], v[238:241], v[48:63]
	ds_read_b64_tr_b16 v[238:239], v189 offset:0x2400
	ds_read_b64_tr_b16 v[240:241], v189 offset:0x2c00
	v_mfma_f32_32x32x16_bf16 v[48:63], v[216:219], v[242:245], v[48:63]
	ds_read_b64_tr_b16 v[242:243], v189 offset:0x3400
	ds_read_b64_tr_b16 v[244:245], v189 offset:0x3c00
	s_waitcnt lgkmcnt(0)
	v_mfma_f32_32x32x16_bf16 v[32:47], v[160:163], v[220:223], v[32:47]
	ds_read_b64_tr_b16 v[220:221], v189 offset:0x600
	ds_read_b64_tr_b16 v[222:223], v189 offset:0xe00
	v_mfma_f32_32x32x16_bf16 v[32:47], v[170:173], v[234:237], v[32:47]
	ds_read_b64_tr_b16 v[234:235], v189 offset:0x1600
	ds_read_b64_tr_b16 v[236:237], v189 offset:0x1e00
	v_mfma_f32_32x32x16_bf16 v[32:47], v[166:169], v[238:241], v[32:47]
	ds_read_b64_tr_b16 v[238:239], v189 offset:0x2600
	ds_read_b64_tr_b16 v[240:241], v189 offset:0x2e00
	v_mfma_f32_32x32x16_bf16 v[32:47], v[216:219], v[242:245], v[32:47]
	ds_read_b64_tr_b16 v[242:243], v189 offset:0x3600
	ds_read_b64_tr_b16 v[244:245], v189 offset:0x3e00
	s_waitcnt lgkmcnt(0)
	v_mfma_f32_32x32x16_bf16 v[16:31], v[160:163], v[220:223], v[16:31]
	v_max_f32_e32 v160, v81, v81
	v_max_f32_e32 v161, v80, v80
	v_max_f32_e32 v160, v161, v160
	v_max3_f32 v160, v160, v82, v83
	v_max3_f32 v160, v160, v84, v85
	v_max3_f32 v160, v160, v86, v87
	v_max3_f32 v160, v160, v88, v89
	v_max3_f32 v160, v160, v90, v91
	v_max3_f32 v160, v160, v92, v93
	v_mfma_f32_32x32x16_bf16 v[16:31], v[170:173], v[234:237], v[16:31]
	v_max3_f32 v160, v160, v94, v95
	v_max3_f32 v160, v160, v64, v65
	v_max3_f32 v160, v160, v66, v67
	v_max3_f32 v160, v160, v68, v69
	v_max3_f32 v160, v160, v70, v71
	v_max3_f32 v160, v160, v72, v73
	v_max3_f32 v160, v160, v74, v75
	v_max3_f32 v160, v160, v76, v77
	v_mfma_f32_32x32x16_bf16 v[16:31], v[166:169], v[238:241], v[16:31]
	v_max3_f32 v160, v160, v78, v79
	v_mov_b32_e32 v161, v160
	s_nop 1
	v_permlane32_swap_b32_e32 v160, v161
	v_max_f32_e32 v161, v161, v161
	v_max_f32_e32 v160, v160, v160
	v_max_f32_e32 v160, v160, v161
	v_sub_f32_e32 v161, v160, v164
	v_cmp_ge_f32_e32 vcc, s18, v161
	v_max_f32_e32 v161, v164, v164
	v_max_f32_e32 v160, v161, v160
	v_mfma_f32_32x32x16_bf16 v[16:31], v[216:219], v[242:245], v[16:31]
	v_sub_f32_e32 v161, v164, v160
	v_mul_f32_e32 v161, 0x3e0293ee, v161
	v_exp_f32_e32 v161, v161
	s_cmp_eq_u64 vcc, exec
	s_cselect_b64 s[0:1], -1, 0
	s_barrier
	s_waitcnt vmcnt(4)
	v_cndmask_b32_e64 v215, v161, 1.0, s[0:1]
	v_cmp_gt_f32_e32 vcc, 1.0, v215
	s_waitcnt vmcnt(7)
	ds_write_b128 v191, v[128:131]
	s_waitcnt vmcnt(6)
	ds_write_b128 v202, v[136:139]
	s_waitcnt vmcnt(5)
	ds_write_b128 v190, v[132:135] offset:32768
	s_waitcnt vmcnt(4)
	ds_write_b128 v203, v[140:143] offset:32768
	s_cbranch_vccz .LBB0_203
	s_and_saveexec_b64 s[2:3], s[36:37]
	ds_write_b32 v186, v215 offset:128
	s_or_b64 exec, exec, s[2:3]
	s_waitcnt lgkmcnt(0)
	v_add_u32_e32 v161, v185, v192
	ds_read_b128 v[166:169], v161 offset:224
	ds_read_b128 v[170:173], v161 offset:192
	ds_read_b128 v[216:219], v161 offset:160
	ds_read_b128 v[220:223], v161 offset:128
	s_waitcnt lgkmcnt(3)
	v_pk_mul_f32 v[12:13], v[12:13], v[166:167]
	s_waitcnt lgkmcnt(2)
	v_pk_mul_f32 v[8:9], v[8:9], v[170:171]
	s_waitcnt lgkmcnt(1)
	v_pk_mul_f32 v[4:5], v[4:5], v[216:217]
	v_pk_mul_f32 v[14:15], v[14:15], v[168:169]
	v_pk_mul_f32 v[10:11], v[10:11], v[172:173]
	v_pk_mul_f32 v[6:7], v[6:7], v[218:219]
	s_waitcnt lgkmcnt(0)
	v_pk_mul_f32 v[2:3], v[2:3], v[222:223]
	v_pk_mul_f32 v[0:1], v[0:1], v[220:221]
	v_pk_mul_f32 v[60:61], v[60:61], v[166:167]
	v_pk_mul_f32 v[56:57], v[56:57], v[170:171]
	v_pk_mul_f32 v[52:53], v[52:53], v[216:217]
	v_pk_mul_f32 v[62:63], v[62:63], v[168:169]
	v_pk_mul_f32 v[58:59], v[58:59], v[172:173]
	v_pk_mul_f32 v[54:55], v[54:55], v[218:219]
	v_pk_mul_f32 v[50:51], v[50:51], v[222:223]
	v_pk_mul_f32 v[48:49], v[48:49], v[220:221]
	v_pk_mul_f32 v[44:45], v[44:45], v[166:167]
	v_pk_mul_f32 v[40:41], v[40:41], v[170:171]
	v_pk_mul_f32 v[36:37], v[36:37], v[216:217]
	v_pk_mul_f32 v[46:47], v[46:47], v[168:169]
	v_pk_mul_f32 v[42:43], v[42:43], v[172:173]
	v_pk_mul_f32 v[38:39], v[38:39], v[218:219]
	v_pk_mul_f32 v[34:35], v[34:35], v[222:223]
	v_pk_mul_f32 v[32:33], v[32:33], v[220:221]
	v_pk_mul_f32 v[28:29], v[28:29], v[166:167]
	v_pk_mul_f32 v[24:25], v[24:25], v[170:171]
	v_pk_mul_f32 v[20:21], v[20:21], v[216:217]
	v_pk_mul_f32 v[30:31], v[30:31], v[168:169]
	v_pk_mul_f32 v[26:27], v[26:27], v[172:173]
	v_pk_mul_f32 v[22:23], v[22:23], v[218:219]
	v_pk_mul_f32 v[18:19], v[18:19], v[222:223]
	v_pk_mul_f32 v[16:17], v[16:17], v[220:221]
; __device__ __forceinline__ void partialSM(f32x16& p0, f32x16& p1, float& m_reg, float& mn, float& alpha) {
;     ...
;   float mnC = -mn * C;
; #pragma unroll
;   for (int r = 0; r < 16; ++r) p0[r] = fmaf(p0[r], C, mnC);
; #pragma unroll
;   for (int r = 0; r < 16; ++r) p1[r] = fmaf(p1[r], C, mnC);
; #pragma unroll
;   for (int r = 0; r < 16; ++r) p0[r] = __builtin_amdgcn_exp2f(p0[r]);
; }
; __device__ __forceinline__ void finishSM(f32x16& p0, f32x16& p1, float alpha, float& l_reg, bf16x8& pa0, bf16x8& pa1, bf16x8& pa2, bf16x8& pa3) {
; #pragma unroll
;   for (int r = 0; r < 16; ++r) p1[r] = __builtin_amdgcn_exp2f(p1[r]);
;   float ps = 0;
; #pragma unroll
;   for (int r = 0; r < 16; ++r) ps += p0[r];
; #pragma unroll
;   for (int r = 0; r < 16; ++r) ps += p1[r];
;   { auto rr = __builtin_amdgcn_permlane32_swap(__float_as_uint(ps), __float_as_uint(ps), false, false);
;     ps = __uint_as_float(rr[0]) + __uint_as_float(rr[1]); }
;   l_reg = l_reg * alpha + ps;
;     ...
;   PK4(p0, 0, pa0); PK4(p0, 8, pa1); PK4(p1, 0, pa2); PK4(p1, 8, pa3);
;     ...
; }
; __device__ __forceinline__ void qkt(f32x16& p0, f32x16& p1, const char* Ks, const bf16x8* qr, int r32, int hi) {
;   p0 = f32x16{}; p1 = f32x16{};
; #pragma unroll
;   for (int d0 = 0; d0 < 8; ++d0) { int cb = (d0 * 16 + hi * 8) * 2;
;     bf16x8 b0 = *reinterpret_cast<const bf16x8*>(Ks + KSWZ(r32, cb));
;     bf16x8 b1 = *reinterpret_cast<const bf16x8*>(Ks + KSWZ(32 + r32, cb));
;     p0 = __builtin_amdgcn_mfma_f32_32x32x16_bf16(b0, qr[d0], p0, 0, 0, 0);
;     p1 = __builtin_amdgcn_mfma_f32_32x32x16_bf16(b1, qr[d0], p1, 0, 0, 0); }
.LBB0_203:
	v_cndmask_b32_e64 v216, v160, v164, s[0:1]
	v_mul_f32_e32 v217, 0xbe0293ee, v216
	v_fmamk_f32 v80, v80, 0x3e0293ee, v217
	v_fmamk_f32 v81, v81, 0x3e0293ee, v217
	v_fmamk_f32 v82, v82, 0x3e0293ee, v217
	v_fmamk_f32 v83, v83, 0x3e0293ee, v217
	v_fmamk_f32 v84, v84, 0x3e0293ee, v217
	v_fmamk_f32 v85, v85, 0x3e0293ee, v217
	v_fmamk_f32 v86, v86, 0x3e0293ee, v217
	v_fmamk_f32 v87, v87, 0x3e0293ee, v217
	v_fmamk_f32 v88, v88, 0x3e0293ee, v217
	v_fmamk_f32 v89, v89, 0x3e0293ee, v217
	v_fmamk_f32 v90, v90, 0x3e0293ee, v217
	v_fmamk_f32 v91, v91, 0x3e0293ee, v217
	v_fmamk_f32 v92, v92, 0x3e0293ee, v217
	v_fmamk_f32 v93, v93, 0x3e0293ee, v217
	v_fmamk_f32 v94, v94, 0x3e0293ee, v217
	v_fmamk_f32 v95, v95, 0x3e0293ee, v217
	v_exp_f32_e32 v160, v80
	v_exp_f32_e32 v161, v81
	v_exp_f32_e32 v162, v82
	v_exp_f32_e32 v173, v83
	v_exp_f32_e32 v174, v84
	v_exp_f32_e32 v175, v85
	v_exp_f32_e32 v163, v86
	v_exp_f32_e32 v172, v87
	v_exp_f32_e32 v164, v88
	v_exp_f32_e32 v165, v89
	v_exp_f32_e32 v170, v90
	v_exp_f32_e32 v171, v91
	v_exp_f32_e32 v166, v92
	v_exp_f32_e32 v167, v93
	v_exp_f32_e32 v168, v94
	v_exp_f32_e32 v169, v95
	v_fmamk_f32 v235, v64, 0x3e0293ee, v217
	v_fmamk_f32 v236, v65, 0x3e0293ee, v217
	v_fmamk_f32 v237, v66, 0x3e0293ee, v217
	v_fmamk_f32 v238, v67, 0x3e0293ee, v217
	v_fmamk_f32 v239, v68, 0x3e0293ee, v217
	v_fmamk_f32 v219, v69, 0x3e0293ee, v217
	v_fmamk_f32 v220, v70, 0x3e0293ee, v217
	v_fmamk_f32 v221, v71, 0x3e0293ee, v217
	v_fmamk_f32 v222, v72, 0x3e0293ee, v217
	v_fmamk_f32 v223, v73, 0x3e0293ee, v217
	v_fmamk_f32 v233, v74, 0x3e0293ee, v217
	v_fmamk_f32 v234, v75, 0x3e0293ee, v217
	v_fmamk_f32 v218, v76, 0x3e0293ee, v217
	v_fmamk_f32 v240, v77, 0x3e0293ee, v217
	v_fmamk_f32 v241, v78, 0x3e0293ee, v217
	v_fmac_f32_e32 v217, 0x3e0293ee, v79
	s_waitcnt lgkmcnt(0)
	s_barrier
	ds_read_b128 v[64:67], v204 offset:32768
	ds_read_b128 v[68:71], v204 offset:40960
	ds_read_b128 v[242:245], v211 offset:32768
	ds_read_b128 v[246:249], v211 offset:40960
	v_exp_f32_e32 v235, v235
	v_exp_f32_e32 v236, v236
	s_waitcnt lgkmcnt(3)
	v_mfma_f32_32x32x16_bf16 v[80:95], v[64:67], v[116:119], 0
	v_exp_f32_e32 v237, v237
	v_exp_f32_e32 v238, v238
	v_exp_f32_e32 v239, v239
	v_exp_f32_e32 v219, v219
	v_exp_f32_e32 v220, v220
	v_exp_f32_e32 v221, v221
	v_exp_f32_e32 v222, v222
	s_waitcnt lgkmcnt(2)
	v_mfma_f32_32x32x16_bf16 v[64:79], v[68:71], v[116:119], 0
	v_exp_f32_e32 v223, v223
	v_exp_f32_e32 v233, v233
	v_exp_f32_e32 v234, v234
	v_exp_f32_e32 v240, v240
	v_exp_f32_e32 v241, v241
	s_waitcnt lgkmcnt(1)
	v_mfma_f32_32x32x16_bf16 v[80:95], v[242:245], v[112:115], v[80:95]
	s_waitcnt lgkmcnt(0)
	v_mfma_f32_32x32x16_bf16 v[64:79], v[246:249], v[112:115], v[64:79]
	ds_read_b128 v[242:245], v210 offset:32768
	ds_read_b128 v[246:249], v210 offset:40960
	s_waitcnt lgkmcnt(1)
	v_mfma_f32_32x32x16_bf16 v[80:95], v[242:245], v[124:127], v[80:95]
	s_waitcnt lgkmcnt(0)
	v_mfma_f32_32x32x16_bf16 v[64:79], v[246:249], v[124:127], v[64:79]
	ds_read_b128 v[242:245], v208 offset:32768
	ds_read_b128 v[246:249], v208 offset:40960
	s_waitcnt lgkmcnt(1)
	v_mfma_f32_32x32x16_bf16 v[80:95], v[242:245], v[120:123], v[80:95]
	s_waitcnt lgkmcnt(0)
	v_mfma_f32_32x32x16_bf16 v[64:79], v[246:249], v[120:123], v[64:79]
	ds_read_b128 v[242:245], v206 offset:32768
	ds_read_b128 v[246:249], v206 offset:40960
	s_waitcnt lgkmcnt(1)
	v_mfma_f32_32x32x16_bf16 v[80:95], v[242:245], v[108:111], v[80:95]
	s_waitcnt lgkmcnt(0)
	v_mfma_f32_32x32x16_bf16 v[64:79], v[246:249], v[108:111], v[64:79]
	ds_read_b128 v[242:245], v205 offset:32768
	ds_read_b128 v[246:249], v205 offset:40960
	s_waitcnt lgkmcnt(1)
	v_mfma_f32_32x32x16_bf16 v[80:95], v[242:245], v[104:107], v[80:95]
	s_waitcnt lgkmcnt(0)
	v_mfma_f32_32x32x16_bf16 v[64:79], v[246:249], v[104:107], v[64:79]
	ds_read_b64_tr_b16 v[128:129], v188 offset:0
	ds_read_b64_tr_b16 v[130:131], v188 offset:0x800
	ds_read_b64_tr_b16 v[132:133], v188 offset:0x1000
	ds_read_b64_tr_b16 v[134:135], v188 offset:0x1800
	ds_read_b64_tr_b16 v[136:137], v188 offset:0x2000
	ds_read_b64_tr_b16 v[138:139], v188 offset:0x2800
	ds_read_b64_tr_b16 v[140:141], v188 offset:0x3000
	ds_read_b64_tr_b16 v[142:143], v188 offset:0x3800
	ds_read_b128 v[242:245], v207 offset:32768
	ds_read_b128 v[246:249], v207 offset:40960
	s_waitcnt lgkmcnt(1)
	v_mfma_f32_32x32x16_bf16 v[80:95], v[242:245], v[100:103], v[80:95]
	s_waitcnt lgkmcnt(0)
	v_mfma_f32_32x32x16_bf16 v[64:79], v[246:249], v[100:103], v[64:79]
	ds_read_b128 v[242:245], v209 offset:32768
	ds_read_b128 v[246:249], v209 offset:40960
	s_waitcnt lgkmcnt(1)
	v_mfma_f32_32x32x16_bf16 v[80:95], v[242:245], v[96:99], v[80:95]
	v_exp_f32_e32 v243, v217
	v_add_f32_e32 v217, 0, v160
	v_add_f32_e32 v217, v161, v217
	v_add_f32_e32 v217, v162, v217
	v_add_f32_e32 v217, v173, v217
	v_add_f32_e32 v217, v174, v217
	v_add_f32_e32 v217, v175, v217
	v_add_f32_e32 v217, v163, v217
	v_add_f32_e32 v217, v172, v217
	v_add_f32_e32 v217, v164, v217
	v_add_f32_e32 v217, v165, v217
	v_add_f32_e32 v217, v170, v217
	v_add_f32_e32 v217, v171, v217
	v_add_f32_e32 v217, v166, v217
	v_add_f32_e32 v217, v167, v217
	v_add_f32_e32 v217, v168, v217
	v_add_f32_e32 v217, v169, v217
	v_add_f32_e32 v217, v235, v217
	v_add_f32_e32 v217, v236, v217
	v_add_f32_e32 v217, v237, v217
	v_add_f32_e32 v217, v238, v217
	v_add_f32_e32 v217, v239, v217
	v_add_f32_e32 v217, v219, v217
	v_add_f32_e32 v217, v220, v217
	v_add_f32_e32 v217, v221, v217
	v_exp_f32_e32 v242, v218
	v_add_f32_e32 v217, v222, v217
	v_add_f32_e32 v217, v223, v217
	s_waitcnt lgkmcnt(0)
; #define SBAR() __builtin_amdgcn_sched_barrier(0)
; __device__ __forceinline__ void finishSM(f32x16& p0, f32x16& p1, float alpha, float& l_reg, bf16x8& pa0, bf16x8& pa1, bf16x8& pa2, bf16x8& pa3) {
;     ...
;   for (int r = 0; r < 16; ++r) ps += p0[r];
; #pragma unroll
;   for (int r = 0; r < 16; ++r) ps += p1[r];
;   { auto rr = __builtin_amdgcn_permlane32_swap(__float_as_uint(ps), __float_as_uint(ps), false, false);
;     ps = __uint_as_float(rr[0]) + __uint_as_float(rr[1]); }
;   l_reg = l_reg * alpha + ps;
;     ...
;   PK4(p0, 0, pa0); PK4(p0, 8, pa1); PK4(p1, 0, pa2); PK4(p1, 8, pa3);
; template <int D0> __device__ __forceinline__ void pv_one(f32x16& od, int vb, bf16x8 pa0, bf16x8 pa1, bf16x8 pa2, bf16x8 pa3) {
;   const s16x4 l0 = tr_read<v_rd_off(D0, 0, 0)>(vb), h0 = tr_read<v_rd_off(D0, 0, 1)>(vb), l1 = tr_read<v_rd_off(D0, 1, 0)>(vb), h1 = tr_read<v_rd_off(D0, 1, 1)>(vb);
;   const s16x4 l2 = tr_read<v_rd_off(D0, 2, 0)>(vb), h2 = tr_read<v_rd_off(D0, 2, 1)>(vb), l3 = tr_read<v_rd_off(D0, 3, 0)>(vb), h3 = tr_read<v_rd_off(D0, 3, 1)>(vb);
;   asm volatile("s_waitcnt lgkmcnt(0)" ::: "memory"); SBAR();
;     ...
;   od = __builtin_amdgcn_mfma_f32_32x32x16_bf16(pa0, PK(l0, h0), od, 0, 0, 0);
;   od = __builtin_amdgcn_mfma_f32_32x32x16_bf16(pa1, PK(l1, h1), od, 0, 0, 0);
;   od = __builtin_amdgcn_mfma_f32_32x32x16_bf16(pa2, PK(l2, h2), od, 0, 0, 0);
;   od = __builtin_amdgcn_mfma_f32_32x32x16_bf16(pa3, PK(l3, h3), od, 0, 0, 0);
;     ...
; }
; __device__ __forceinline__ void pv_d0(f32x16* o, int vb, bf16x8 pa0, bf16x8 pa1, bf16x8 pa2, bf16x8 pa3) {
;   pv_one<0>(o[0], vb, pa0, pa1, pa2, pa3); pv_one<1>(o[1], vb, pa0, pa1, pa2, pa3); pv_one<2>(o[2], vb, pa0, pa1, pa2, pa3); pv_one<3>(o[3], vb, pa0, pa1, pa2, pa3);
	v_mfma_f32_32x32x16_bf16 v[64:79], v[246:249], v[96:99], v[64:79]
	v_add_f32_e32 v217, v233, v217
	v_add_f32_e32 v217, v234, v217
	v_add_f32_e32 v217, v242, v217
	v_add_f32_e32 v217, v240, v217
	v_add_f32_e32 v217, v241, v217
	v_add_f32_e32 v217, v243, v217
	v_mov_b32_e32 v218, v217
	v_cvt_pk_bf16_f32 v160, v160, v161
	v_cvt_pk_bf16_f32 v161, v162, v173
	v_cvt_pk_bf16_f32 v162, v174, v175
	v_cvt_pk_bf16_f32 v163, v163, v172
	v_cvt_pk_bf16_f32 v164, v164, v165
	v_cvt_pk_bf16_f32 v165, v170, v171
	v_cvt_pk_bf16_f32 v166, v166, v167
	v_cvt_pk_bf16_f32 v167, v168, v169
	v_cvt_pk_bf16_f32 v168, v235, v236
	v_cvt_pk_bf16_f32 v169, v237, v238
	v_cvt_pk_bf16_f32 v170, v239, v219
	v_cvt_pk_bf16_f32 v171, v220, v221
	v_cvt_pk_bf16_f32 v172, v222, v223
	v_cvt_pk_bf16_f32 v173, v233, v234
	v_cvt_pk_bf16_f32 v174, v242, v240
	v_cvt_pk_bf16_f32 v175, v241, v243
	v_permlane32_swap_b32_e32 v217, v218
	v_permlane32_swap_b32_e32 v160, v162
	v_permlane32_swap_b32_e32 v161, v163
	v_permlane32_swap_b32_e32 v164, v166
	v_permlane32_swap_b32_e32 v165, v167
	v_permlane32_swap_b32_e32 v168, v170
	v_permlane32_swap_b32_e32 v169, v171
	v_permlane32_swap_b32_e32 v172, v174
	v_permlane32_swap_b32_e32 v173, v175
	s_waitcnt lgkmcnt(0)
	s_nop 0
	v_mfma_f32_32x32x16_bf16 v[0:15], v[160:163], v[128:131], v[0:15]
	ds_read_b64_tr_b16 v[220:221], v188 offset:0x200
	ds_read_b64_tr_b16 v[222:223], v188 offset:0xa00
	v_mfma_f32_32x32x16_bf16 v[0:15], v[164:167], v[132:135], v[0:15]
	ds_read_b64_tr_b16 v[234:235], v188 offset:0x1200
	ds_read_b64_tr_b16 v[236:237], v188 offset:0x1a00
	v_mfma_f32_32x32x16_bf16 v[0:15], v[168:171], v[136:139], v[0:15]
	ds_read_b64_tr_b16 v[238:239], v188 offset:0x2200
	ds_read_b64_tr_b16 v[240:241], v188 offset:0x2a00
	v_mfma_f32_32x32x16_bf16 v[0:15], v[172:175], v[140:143], v[0:15]
	ds_read_b64_tr_b16 v[242:243], v188 offset:0x3200
	ds_read_b64_tr_b16 v[244:245], v188 offset:0x3a00
	s_cmpk_gt_u32 s20, 0x7c
	s_cselect_b64 s[2:3], -1, 0
	s_and_b64 vcc, exec, s[2:3]
	s_cbranch_vccnz .Lgq_noprefetch
	global_load_dwordx4 v[128:131], v178, s[6:7]
	global_load_dwordx4 v[132:135], v178, s[4:5]
	global_load_dwordx4 v[136:139], v179, s[6:7]
	global_load_dwordx4 v[140:143], v179, s[4:5]
; #define SBAR() __builtin_amdgcn_sched_barrier(0)
; #define SLOAD(i, k0) do { sr_[i].vs0 = *(const bf16x8*)(&Vh[(long)((k0) + sr) * LDK + sc]); sr_[i].vs1 = *(const bf16x8*)(&Vh[(long)((k0) + 32 + sr) * LDK + sc]); \
;     sr_[i].ks0 = *(const bf16x8*)(&Kh[(long)((k0) + sr) * LDK + sc]); sr_[i].ks1 = *(const bf16x8*)(&Kh[(long)((k0) + 32 + sr) * LDK + sc]); } while (0)
; #define SWRITE(b, i) do { *(bf16x8*)(V_lds + (b) * SHM_V + vst0) = sr_[i].vs0;          \
;     *(bf16x8*)(V_lds + (b) * SHM_V + vst1) = sr_[i].vs1; int kc = sc * 2;               \
;     *(bf16x8*)(K_lds + (b) * SHM_K + KSWZ(sr, kc)) = sr_[i].ks0;                       \
;     *(bf16x8*)(K_lds + (b) * SHM_K + KSWZ(32 + sr, kc)) = sr_[i].ks1; } while (0)
; #define SWAIT() do { if constexpr (SDEPTH == 2) asm volatile("s_waitcnt vmcnt(4)" ::: "memory"); else asm volatile("s_waitcnt vmcnt(0)" ::: "memory"); } while (0)
; __device__ __forceinline__ void partialSM(f32x16& p0, f32x16& p1, float& m_reg, float& mn, float& alpha) {
;   constexpr float C = SCALE * 1.4426950408889634f;
;   float pmax = p0[0];
; #pragma unroll
;   for (int r = 1; r < 16; ++r) pmax = fmaxf(pmax, p0[r]);
; #pragma unroll
;   for (int r = 0; r < 16; ++r) pmax = fmaxf(pmax, p1[r]);
;   { auto rr = __builtin_amdgcn_permlane32_swap(__float_as_uint(pmax), __float_as_uint(pmax), false, false);
;     pmax = fmaxf(__uint_as_float(rr[0]), __uint_as_float(rr[1])); }
;   if (__builtin_expect(__all(pmax - m_reg <= THR / SCALE), 1)) { mn = m_reg; alpha = 1.f; }
;   else { mn = fmaxf(m_reg, pmax); alpha = __builtin_amdgcn_exp2f((m_reg - mn) * C); m_reg = mn; }
;   float mnC = -mn * C;
; #pragma unroll
;   for (int r = 0; r < 16; ++r) p0[r] = fmaf(p0[r], C, mnC);
; #pragma unroll
;   for (int r = 0; r < 16; ++r) p1[r] = fmaf(p1[r], C, mnC);
; template <int MODE, int SDEPTH, bool SIMPLE>
; __device__ __forceinline__ void attn_body(const Unit& U, char* lds, const int tid) {
;     ...
;     SBAR(); qkt(pA0, pA1, K_lds, qr, r32, hi); amask<MODE>(pA0, pA1, j + 1, U, wid, r32, hi, tbl);
;     finishSM(pB0, pB1, alB, l_reg, pa0, pa1, pa2, pa3); SBAR();
;     if (SDEPTH == 1 || j + 3 < NT) SLOAD(SE, (j + 1 + SDEPTH) * KVBLK); SBAR();
;     pv_d0(o, vb0 + (int)SHM_V, pa0, pa1, pa2, pa3); partialSM(pA0, pA1, m_reg, mnA, alA);
;     __syncthreads(); SWAIT(); SWRITE(1, SO);
;     RESC(alA); __syncthreads();
.LBB0_205:
	s_add_u32 s6, s6, 0x4000
	s_addc_u32 s7, s7, 0
	s_add_u32 s4, s4, 0x4000
	s_addc_u32 s5, s5, 0
	s_waitcnt lgkmcnt(0)
	v_mfma_f32_32x32x16_bf16 v[48:63], v[160:163], v[220:223], v[48:63]
	ds_read_b64_tr_b16 v[220:221], v188 offset:0x400
	ds_read_b64_tr_b16 v[222:223], v188 offset:0xc00
	v_mfma_f32_32x32x16_bf16 v[48:63], v[164:167], v[234:237], v[48:63]
	ds_read_b64_tr_b16 v[234:235], v188 offset:0x1400
	ds_read_b64_tr_b16 v[236:237], v188 offset:0x1c00
	v_mfma_f32_32x32x16_bf16 v[48:63], v[168:171], v[238:241], v[48:63]
	ds_read_b64_tr_b16 v[238:239], v188 offset:0x2400
	ds_read_b64_tr_b16 v[240:241], v188 offset:0x2c00
	v_mfma_f32_32x32x16_bf16 v[48:63], v[172:175], v[242:245], v[48:63]
	ds_read_b64_tr_b16 v[242:243], v188 offset:0x3400
	ds_read_b64_tr_b16 v[244:245], v188 offset:0x3c00
	s_waitcnt lgkmcnt(0)
	v_mfma_f32_32x32x16_bf16 v[32:47], v[160:163], v[220:223], v[32:47]
	ds_read_b64_tr_b16 v[220:221], v188 offset:0x600
	ds_read_b64_tr_b16 v[222:223], v188 offset:0xe00
	v_mfma_f32_32x32x16_bf16 v[32:47], v[164:167], v[234:237], v[32:47]
	ds_read_b64_tr_b16 v[234:235], v188 offset:0x1600
	ds_read_b64_tr_b16 v[236:237], v188 offset:0x1e00
	v_mfma_f32_32x32x16_bf16 v[32:47], v[168:171], v[238:241], v[32:47]
	ds_read_b64_tr_b16 v[238:239], v188 offset:0x2600
	ds_read_b64_tr_b16 v[240:241], v188 offset:0x2e00
	v_mfma_f32_32x32x16_bf16 v[32:47], v[172:175], v[242:245], v[32:47]
	ds_read_b64_tr_b16 v[242:243], v188 offset:0x3600
	ds_read_b64_tr_b16 v[244:245], v188 offset:0x3e00
	s_waitcnt lgkmcnt(0)
	v_mfma_f32_32x32x16_bf16 v[16:31], v[160:163], v[220:223], v[16:31]
	v_max_f32_e32 v160, v81, v81
	v_max_f32_e32 v161, v80, v80
	v_max_f32_e32 v160, v161, v160
	v_max3_f32 v160, v160, v82, v83
	v_max3_f32 v160, v160, v84, v85
	v_max3_f32 v160, v160, v86, v87
	v_max3_f32 v160, v160, v88, v89
	v_max3_f32 v160, v160, v90, v91
	v_max3_f32 v160, v160, v92, v93
	v_mfma_f32_32x32x16_bf16 v[16:31], v[164:167], v[234:237], v[16:31]
	v_max3_f32 v160, v160, v94, v95
	v_max3_f32 v160, v160, v64, v65
	v_max3_f32 v160, v160, v66, v67
	v_max3_f32 v160, v160, v68, v69
	v_max3_f32 v160, v160, v70, v71
	v_max3_f32 v160, v160, v72, v73
	v_max3_f32 v160, v160, v74, v75
	v_max3_f32 v160, v160, v76, v77
	v_mfma_f32_32x32x16_bf16 v[16:31], v[168:171], v[238:241], v[16:31]
	v_max3_f32 v160, v160, v78, v79
	v_mov_b32_e32 v161, v160
	s_nop 1
	v_permlane32_swap_b32_e32 v160, v161
	v_max_f32_e32 v161, v161, v161
	v_max_f32_e32 v160, v160, v160
	v_max_f32_e32 v160, v160, v161
	v_sub_f32_e32 v161, v160, v216
	v_cmp_ge_f32_e32 vcc, s18, v161
	v_max_f32_e32 v161, v216, v216
	v_max_f32_e32 v161, v161, v160
	v_mfma_f32_32x32x16_bf16 v[16:31], v[172:175], v[242:245], v[16:31]
	v_sub_f32_e32 v160, v216, v161
	v_mul_f32_e32 v160, 0x3e0293ee, v160
	v_exp_f32_e32 v160, v160
	s_cmp_eq_u64 vcc, exec
	s_cselect_b64 s[0:1], -1, 0
	s_barrier
	s_waitcnt vmcnt(4)
	v_cndmask_b32_e64 v160, v160, 1.0, s[0:1]
	v_cmp_gt_f32_e32 vcc, 1.0, v160
	ds_write_b128 v191, v[144:147] offset:16384
	ds_write_b128 v202, v[148:151] offset:16384
	ds_write_b128 v190, v[152:155] offset:49152
	ds_write_b128 v203, v[156:159] offset:49152
	s_cbranch_vccz .LBB0_209
	s_and_saveexec_b64 s[42:43], s[36:37]
	ds_write_b32 v186, v160 offset:128
	s_or_b64 exec, exec, s[42:43]
	s_waitcnt lgkmcnt(0)
	v_add_u32_e32 v156, v185, v192
	ds_read_b128 v[144:147], v156 offset:224
	ds_read_b128 v[148:151], v156 offset:192
	ds_read_b128 v[152:155], v156 offset:160
	ds_read_b128 v[156:159], v156 offset:128
	s_waitcnt lgkmcnt(3)
	v_pk_mul_f32 v[12:13], v[12:13], v[144:145]
	s_waitcnt lgkmcnt(2)
	v_pk_mul_f32 v[8:9], v[8:9], v[148:149]
	s_waitcnt lgkmcnt(1)
	v_pk_mul_f32 v[4:5], v[4:5], v[152:153]
	v_pk_mul_f32 v[14:15], v[14:15], v[146:147]
	v_pk_mul_f32 v[10:11], v[10:11], v[150:151]
	v_pk_mul_f32 v[6:7], v[6:7], v[154:155]
	s_waitcnt lgkmcnt(0)
	v_pk_mul_f32 v[2:3], v[2:3], v[158:159]
	v_pk_mul_f32 v[0:1], v[0:1], v[156:157]
	v_pk_mul_f32 v[60:61], v[60:61], v[144:145]
	v_pk_mul_f32 v[56:57], v[56:57], v[148:149]
	v_pk_mul_f32 v[52:53], v[52:53], v[152:153]
	v_pk_mul_f32 v[62:63], v[62:63], v[146:147]
	v_pk_mul_f32 v[58:59], v[58:59], v[150:151]
	v_pk_mul_f32 v[54:55], v[54:55], v[154:155]
	v_pk_mul_f32 v[50:51], v[50:51], v[158:159]
	v_pk_mul_f32 v[48:49], v[48:49], v[156:157]
	v_pk_mul_f32 v[44:45], v[44:45], v[144:145]
	v_pk_mul_f32 v[40:41], v[40:41], v[148:149]
	v_pk_mul_f32 v[36:37], v[36:37], v[152:153]
	v_pk_mul_f32 v[46:47], v[46:47], v[146:147]
	v_pk_mul_f32 v[42:43], v[42:43], v[150:151]
	v_pk_mul_f32 v[38:39], v[38:39], v[154:155]
	v_pk_mul_f32 v[34:35], v[34:35], v[158:159]
	v_pk_mul_f32 v[32:33], v[32:33], v[156:157]
	v_pk_mul_f32 v[28:29], v[28:29], v[144:145]
	v_pk_mul_f32 v[24:25], v[24:25], v[148:149]
	v_pk_mul_f32 v[20:21], v[20:21], v[152:153]
	v_pk_mul_f32 v[30:31], v[30:31], v[146:147]
	v_pk_mul_f32 v[26:27], v[26:27], v[150:151]
	v_pk_mul_f32 v[22:23], v[22:23], v[154:155]
	v_pk_mul_f32 v[18:19], v[18:19], v[158:159]
	v_pk_mul_f32 v[16:17], v[16:17], v[156:157]
.LBB0_209:
	v_cndmask_b32_e64 v164, v161, v216, s[0:1]
	v_mul_f32_e32 v150, 0xbe0293ee, v164
	v_mov_b32_e32 v151, v150
	v_fmamk_f32 v80, v80, 0x3e0293ee, v150
	v_fmamk_f32 v81, v81, 0x3e0293ee, v150
	v_fmamk_f32 v82, v82, 0x3e0293ee, v150
	v_fmamk_f32 v83, v83, 0x3e0293ee, v150
	v_fmamk_f32 v84, v84, 0x3e0293ee, v150
	v_fmamk_f32 v85, v85, 0x3e0293ee, v150
	v_fmamk_f32 v86, v86, 0x3e0293ee, v150
	v_fmamk_f32 v87, v87, 0x3e0293ee, v150
	v_fmamk_f32 v88, v88, 0x3e0293ee, v150
	v_fmamk_f32 v89, v89, 0x3e0293ee, v150
	v_fmamk_f32 v90, v90, 0x3e0293ee, v150
	v_fmamk_f32 v91, v91, 0x3e0293ee, v150
	v_fmamk_f32 v92, v92, 0x3e0293ee, v150
	v_fmamk_f32 v93, v93, 0x3e0293ee, v150
	v_fmamk_f32 v94, v94, 0x3e0293ee, v150
	v_fmac_f32_e32 v151, 0x3e0293ee, v95
	v_exp_f32_e32 v161, v80
	v_exp_f32_e32 v162, v81
	v_exp_f32_e32 v174, v82
	v_exp_f32_e32 v175, v83
	v_exp_f32_e32 v216, v84
	v_exp_f32_e32 v219, v85
	v_exp_f32_e32 v163, v86
	v_exp_f32_e32 v173, v87
	v_exp_f32_e32 v168, v88
	v_exp_f32_e32 v170, v89
	v_exp_f32_e32 v171, v90
	v_exp_f32_e32 v172, v91
	v_exp_f32_e32 v165, v92
	v_exp_f32_e32 v166, v93
	v_exp_f32_e32 v167, v94
	v_exp_f32_e32 v169, v151
	v_pk_fma_f32 v[156:157], v[64:65], s[12:13], v[150:151] op_sel_hi:[1,0,0]
	v_add_f32_e32 v64, v213, v214
	v_fmac_f32_e32 v64, v212, v187
	v_add_f32_e32 v187, v217, v218
	v_pk_fma_f32 v[154:155], v[66:67], s[12:13], v[150:151] op_sel_hi:[1,0,0]
	v_pk_fma_f32 v[148:149], v[68:69], s[12:13], v[150:151] op_sel_hi:[1,0,0]
	v_pk_fma_f32 v[146:147], v[70:71], s[12:13], v[150:151] op_sel_hi:[1,0,0]
	v_pk_fma_f32 v[144:145], v[72:73], s[12:13], v[150:151] op_sel_hi:[1,0,0]
	v_pk_fma_f32 v[158:159], v[74:75], s[12:13], v[150:151] op_sel_hi:[1,0,0]
	v_pk_fma_f32 v[152:153], v[76:77], s[12:13], v[150:151] op_sel_hi:[1,0,0]
	v_pk_fma_f32 v[150:151], v[78:79], s[12:13], v[150:151] op_sel_hi:[1,0,0]
	v_fmac_f32_e32 v187, v64, v215
	s_add_i32 s20, s20, 2
	s_and_b64 vcc, exec, s[2:3]
	s_waitcnt lgkmcnt(0)
	s_barrier
	s_cbranch_vccnz .LBB0_211
	v_mov_b32_e32 v212, v160
	s_branch .LBB0_199

; __device__ __forceinline__ int opaque_v(int v) { asm volatile("" : "+v"(v)); return v; }
; __global__ void __launch_bounds__(512) mega(Args a) {
;     ...
;       for (int i = 0;; ++i) {
;         const int un = i * G + cu; if (un >= NB * 8 * 32) break;
;         const int h = un & 7, qb = (un >> 3) & 31, b = un >> 8;
;         __syncthreads();
;         att::Unit U{};
;         const size_t tq = (size_t)b * SEQ + qb * 256;
;         U.Q = QBc + ((size_t)(b * 8 + h) * SEQ + qb * 256) * 128; U.K = KBc + (size_t)(b * 2 + (h >> 2)) * SEQ * 128; U.V = VBc + (size_t)(b * 2 + (h >> 2)) * SEQ * 128;
;         U.ldq = 128; U.ldk = 128; U.NT = SEQ / 64;
;         U.O = Y + tq * YW + 1024 + h * 128; U.ldo = YW; U.Z = PROJ + tq * NIN + C_ZB + h * 128; U.ldz = NIN;
;         att::attn_body<0, 2, false>(U, shm, opaque_v(tid));
;       }
.Lgq_restore:
	v_readlane_b32 s4, v250, 16
	v_readlane_b32 s5, v250, 17
	v_readlane_b32 s6, v250, 18
	v_readlane_b32 s7, v250, 19
	v_readlane_b32 s66, v250, 20
	v_readlane_b32 s67, v250, 21
	s_branch .LBB0_217
